# proj phase: per-tile alternating priority raise between the two co-resident workgroups (plus static raise in attention)
# baseline (speedup 1.0000x reference)
; DI f32x16 zero16() { f32x16 z; _Pragma("unroll") for (int i = 0; i < 16; ++i) z[i] = 0.f; return z; }
; #define G_LOAD(KOFF) do { rw0 = *(const uint4*)(gw + (KOFF)); rw1 = *(const uint4*)(gw1 + (KOFF)); rw2 = *(const uint4*)(gw2 + (KOFF)); rw3 = *(const uint4*)(gw3 + (KOFF)); \
;                           rx0 = *(const uint4*)(gx + (KOFF)); rx1 = *(const uint4*)(gx1 + (KOFF)); rx2 = *(const uint4*)(gx2 + (KOFF)); rx3 = *(const uint4*)(gx3 + (KOFF)); } while (0)
; DI void gemm128(const u16* __restrict__ W, int ldw, const u16* __restrict__ X, int ldx, int K, f32x16 (&acc)[2][2], char* smem) {
;     ...
;   const u16* gw = W + (size_t)lr * ldw + lc * 8;
;   const u16* gx = X + (size_t)lr * ldx + lc * 8;
;   const u16* gw1 = gw + (size_t)32 * ldw; const u16* gw2 = gw + (size_t)64 * ldw; const u16* gw3 = gw + (size_t)96 * ldw;
;   const u16* gx1 = gx + (size_t)32 * ldx; const u16* gx2 = gx + (size_t)64 * ldx; const u16* gx3 = gx + (size_t)96 * ldx;
;   uint4 rw0, rw1, rw2, rw3, rx0, rx1, rx2, rx3;
;     ...
;   G_LOAD(0);
;   G_STORE(0);
;   const int nk = K >> 6;
;   G_LOAD(64);
; DI void phase_proj(const Params& p, int layer, char* smem, int xcd, int loc, int nloc) {
;     ...
;     const int m0 = mt * 128, n0 = nt * 128;
;     f32x16 acc[2][2];
;     acc[0][0] = zero16(); acc[0][1] = zero16(); acc[1][0] = zero16(); acc[1][1] = zero16();
;     float rinv2[2];
; #pragma unroll
;     for (int mi = 0; mi < 2; ++mi) {
;       const float4* sp = (const float4*)(XSS + (size_t)(m0 + wm * 64 + mi * 32 + r) * 16);
;       float4 q0 = sp[0], q1 = sp[1], q2 = sp[2], q3 = sp[3];
;       float ss = ((q0.x + q0.y) + (q0.z + q0.w)) + ((q1.x + q1.y) + (q1.z + q1.w)) + ((q2.x + q2.y) + (q2.z + q2.w)) + ((q3.x + q3.y) + (q3.z + q3.w));
;       rinv2[mi] = rsqrtf(ss * (1.f / 1024.f) + EPS);
;     }
;     gemm128(WT + (size_t)n0 * LDX, LDX, XB + (size_t)m0 * LDX, LDX, 1024, acc, smem);
.LBB0_1414:
	s_getreg_b32 s10, hwreg(HW_REG_LDS_ALLOC, 0, 8)
	s_cmp_lg_u32 s10, 0
	s_cselect_b32 s10, 1, 0
	s_lshr_b32 s11, s40, 6
	s_xor_b32 s10, s10, s11
	s_bitcmp1_b32 s10, 0
	s_cbranch_scc0 .Lpp0
	s_setprio 1
	s_branch .Lpp1
.Lpp0:
	s_setprio 0
.Lpp1:
	s_lshl_b32 s10, s41, 7
	v_add_u32_e32 v20, s10, v106
	v_ashrrev_i32_e32 v21, 31, v20
	v_readlane_b32 s18, v252, 36
	v_lshlrev_b64 v[4:5], 6, v[20:21]
	v_readlane_b32 s19, v252, 37
	v_or_b32_e32 v20, 32, v20
	v_ashrrev_i32_e32 v21, 31, v20
	v_lshl_add_u64 v[16:17], s[18:19], 0, v[4:5]
	global_load_dwordx4 v[4:7], v[16:17], off
	global_load_dwordx4 v[8:11], v[16:17], off offset:16
	global_load_dwordx4 v[12:15], v[16:17], off offset:32
	s_lshl_b32 s15, s50, 7
	global_load_dwordx4 v[16:19], v[16:17], off offset:48
	s_mul_i32 s7, s50, 0x44000
	v_lshlrev_b64 v[20:21], 6, v[20:21]
	s_mul_hi_i32 s11, s15, 0x880
	s_add_u32 s12, s5, s7
	v_lshl_add_u64 v[32:33], s[18:19], 0, v[20:21]
	v_mov_b32_e32 v104, v128
	s_addc_u32 s13, s30, s11
	global_load_dwordx4 v[20:23], v[32:33], off offset:16
	global_load_dwordx4 v[24:27], v[32:33], off
	v_mov_b64_e32 v[36:37], s[12:13]
	global_load_dwordx4 v[28:31], v[32:33], off offset:32
	s_nop 0
	global_load_dwordx4 v[32:35], v[32:33], off offset:48
	v_mov_b32_e32 v69, v3
	v_ashrrev_i32_e32 v105, 3, v104
	v_lshlrev_b32_e32 v40, 4, v104
	v_mad_i64_i32 v[36:37], s[12:13], v105, s24, v[36:37]
	v_and_b32_e32 v68, 0x70, v40
	v_lshl_add_u64 v[102:103], v[36:37], 0, v[68:69]
	s_mul_i32 s6, s41, 0x44000
	v_add_co_u32_e32 v72, vcc, s38, v102
	s_mul_hi_i32 s7, s10, 0x880
	s_add_u32 s18, s22, s6
	v_addc_co_u32_e32 v73, vcc, 0, v103, vcc
	s_addc_u32 s19, s23, s7
	v_add_co_u32_e32 v76, vcc, s39, v102
	v_mov_b64_e32 v[38:39], s[18:19]
	s_nop 0
	v_addc_co_u32_e32 v77, vcc, 0, v103, vcc
	v_mad_i64_i32 v[38:39], s[12:13], v105, s24, v[38:39]
	v_add_co_u32_e32 v80, vcc, s42, v102
	v_lshl_add_u64 v[84:85], v[38:39], 0, v[68:69]
	s_nop 0
	v_addc_co_u32_e32 v81, vcc, 0, v103, vcc
	v_add_co_u32_e32 v88, vcc, s38, v84
	global_load_dwordx4 v[36:39], v[102:103], off
	global_load_dwordx4 v[40:43], v[84:85], off
	v_addc_co_u32_e32 v89, vcc, 0, v85, vcc
	v_add_co_u32_e32 v92, vcc, s39, v84
	global_load_dwordx4 v[44:47], v[72:73], off
	global_load_dwordx4 v[48:51], v[76:77], off
	global_load_dwordx4 v[52:55], v[80:81], off
	v_addc_co_u32_e32 v93, vcc, 0, v85, vcc
	v_add_co_u32_e32 v96, vcc, s42, v84
	global_load_dwordx4 v[56:59], v[88:89], off
	global_load_dwordx4 v[60:63], v[92:93], off
	v_addc_co_u32_e32 v97, vcc, 0, v85, vcc
	global_load_dwordx4 v[64:67], v[96:97], off
	v_mad_u64_u32 v[100:101], s[12:13], v105, s2, v[68:69]
	global_load_dwordx4 v[80:83], v[80:81], off offset:128
	s_mov_b32 s11, 0x800000
	global_load_dwordx4 v[84:87], v[84:85], off offset:128
	v_readfirstlane_b32 s14, v104
	global_load_dwordx4 v[88:91], v[88:89], off offset:128
	s_lshr_b32 s12, s14, 1
	global_load_dwordx4 v[92:95], v[92:93], off offset:128
	s_and_b32 s16, s14, 64
	s_and_b32 s12, s12, 0xfffffc0
	s_mulk_i32 s16, 0x90
	s_mulk_i32 s12, 0x90
	global_load_dwordx4 v[76:79], v[76:77], off offset:128
	s_waitcnt vmcnt(20)
	v_mov_b32_e32 v70, v5
	v_mov_b32_e32 v71, v6
	s_waitcnt vmcnt(19)
	v_mov_b32_e32 v74, v9
	v_mov_b32_e32 v75, v10
	v_mov_b32_e32 v5, v7
	v_mov_b32_e32 v9, v11
	v_pk_add_f32 v[4:5], v[70:71], v[4:5]
	v_pk_add_f32 v[8:9], v[74:75], v[8:9]
	global_load_dwordx4 v[68:71], v[102:103], off offset:128
	s_waitcnt vmcnt(19)
	v_mov_b32_e32 v6, v13
	global_load_dwordx4 v[72:75], v[72:73], off offset:128
	v_mov_b32_e32 v10, v15
	global_load_dwordx4 v[96:99], v[96:97], off offset:128
	v_pk_add_f32 v[6:7], v[12:13], v[6:7]
	v_pk_add_f32 v[10:11], v[14:15], v[10:11]
	v_pk_add_f32 v[4:5], v[4:5], v[4:5] op_sel:[0,1] op_sel_hi:[1,0]
	v_pk_add_f32 v[8:9], v[8:9], v[8:9] op_sel:[0,1] op_sel_hi:[1,0]
	s_waitcnt vmcnt(20)
	v_mov_b32_e32 v7, v18
	v_mov_b32_e32 v5, v16
	v_mov_b32_e32 v9, v17
	v_mov_b32_e32 v11, v19
	v_pk_add_f32 v[4:5], v[4:5], v[8:9]
	v_pk_add_f32 v[6:7], v[6:7], v[10:11]
	s_waitcnt vmcnt(17)
	v_mov_b32_e32 v8, v29
	v_pk_add_f32 v[4:5], v[4:5], v[6:7]
	v_mov_b32_e32 v6, v21
	v_add_f32_e32 v4, v4, v5
	v_fmamk_f32 v4, v4, 0x3a800000, v206
	v_mul_f32_e32 v5, 0x4b800000, v4
	v_cmp_gt_f32_e64 s[46:47], s11, v4
	v_mov_b32_e32 v7, v22
	v_mov_b32_e32 v21, v23
	v_cndmask_b32_e64 v4, v4, v5, s[46:47]
	v_rsq_f32_e32 v119, v4
	v_mov_b32_e32 v4, v25
	v_mov_b32_e32 v5, v26
	v_mov_b32_e32 v25, v27
	v_pk_add_f32 v[4:5], v[4:5], v[24:25]
	v_pk_add_f32 v[6:7], v[6:7], v[20:21]
	v_mov_b32_e32 v10, v31
	v_pk_add_f32 v[4:5], v[4:5], v[4:5] op_sel:[0,1] op_sel_hi:[1,0]
	v_pk_add_f32 v[6:7], v[6:7], v[6:7] op_sel:[0,1] op_sel_hi:[1,0]
	v_pk_add_f32 v[8:9], v[28:29], v[8:9]
	v_pk_add_f32 v[10:11], v[30:31], v[10:11]
	s_waitcnt vmcnt(16)
; DI f32x16 zero16() { f32x16 z; _Pragma("unroll") for (int i = 0; i < 16; ++i) z[i] = 0.f; return z; }
; #define G_LOAD(KOFF) do { rw0 = *(const uint4*)(gw + (KOFF)); rw1 = *(const uint4*)(gw1 + (KOFF)); rw2 = *(const uint4*)(gw2 + (KOFF)); rw3 = *(const uint4*)(gw3 + (KOFF)); \
;                           rx0 = *(const uint4*)(gx + (KOFF)); rx1 = *(const uint4*)(gx1 + (KOFF)); rx2 = *(const uint4*)(gx2 + (KOFF)); rx3 = *(const uint4*)(gx3 + (KOFF)); } while (0)
; DI void gemm128(const u16* __restrict__ W, int ldw, const u16* __restrict__ X, int ldx, int K, f32x16 (&acc)[2][2], char* smem) {
;     ...
;   G_LOAD(0);
;   G_STORE(0);
;   const int nk = K >> 6;
;   G_LOAD(64);
;   __syncthreads();
; DI void phase_proj(const Params& p, int layer, char* smem, int xcd, int loc, int nloc) {
;     ...
;     acc[0][0] = zero16(); acc[0][1] = zero16(); acc[1][0] = zero16(); acc[1][1] = zero16();
;     float rinv2[2];
; #pragma unroll
;     for (int mi = 0; mi < 2; ++mi) {
;       const float4* sp = (const float4*)(XSS + (size_t)(m0 + wm * 64 + mi * 32 + r) * 16);
;       float4 q0 = sp[0], q1 = sp[1], q2 = sp[2], q3 = sp[3];
;       float ss = ((q0.x + q0.y) + (q0.z + q0.w)) + ((q1.x + q1.y) + (q1.z + q1.w)) + ((q2.x + q2.y) + (q2.z + q2.w)) + ((q3.x + q3.y) + (q3.z + q3.w));
;       rinv2[mi] = rsqrtf(ss * (1.f / 1024.f) + EPS);
	v_mov_b32_e32 v5, v32
	v_mov_b32_e32 v7, v33
	v_mov_b32_e32 v9, v34
	v_mov_b32_e32 v11, v35
	v_pk_add_f32 v[4:5], v[4:5], v[6:7]
	v_pk_add_f32 v[6:7], v[8:9], v[10:11]
	s_waitcnt vmcnt(15)
	ds_write_b128 v100, v[36:39]
	v_pk_add_f32 v[4:5], v[4:5], v[6:7]
	v_and_b32_e32 v6, 7, v104
	v_add_f32_e32 v4, v4, v5
	v_fmamk_f32 v4, v4, 0x3a800000, v206
	v_mul_f32_e32 v5, 0x4b800000, v4
	v_cmp_gt_f32_e64 s[44:45], s11, v4
	s_mov_b32 s11, 0
	s_waitcnt vmcnt(13)
	ds_write_b128 v100, v[44:47] offset:4608
	v_cndmask_b32_e64 v4, v4, v5, s[44:45]
	v_rsq_f32_e32 v118, v4
	v_and_b32_e32 v4, 31, v104
	v_lshrrev_b32_e32 v5, 1, v104
	v_mul_u32_u24_e32 v4, 0x90, v4
	v_and_b32_e32 v5, 16, v5
	v_add3_u32 v101, s16, v4, v5
	v_add3_u32 v120, s12, v4, v5
	v_mov_b64_e32 v[4:5], s[6:7]
	v_mad_i64_i32 v[4:5], s[6:7], v105, s24, v[4:5]
	v_lshl_or_b32 v4, v6, 4, v4
	v_lshl_add_u64 v[104:105], s[94:95], 0, v[4:5]
	v_mov_b32_e32 v4, 0
	s_waitcnt vmcnt(12)
	ds_write_b128 v100, v[48:51] offset:9216
	s_waitcnt vmcnt(11)
	ds_write_b128 v100, v[52:55] offset:13824
	ds_write_b128 v100, v[40:43] offset:36864
	s_waitcnt vmcnt(10)
	ds_write_b128 v100, v[56:59] offset:41472
	s_waitcnt vmcnt(9)
	ds_write_b128 v100, v[60:63] offset:46080
	s_waitcnt vmcnt(8)
	ds_write_b128 v100, v[64:67] offset:50688
	s_mov_b64 s[6:7], 0
	v_mov_b32_e32 v5, v4
	v_mov_b32_e32 v6, v4
	v_mov_b32_e32 v7, v4
	v_mov_b32_e32 v8, v4
	v_mov_b32_e32 v9, v4
	v_mov_b32_e32 v10, v4
	v_mov_b32_e32 v11, v4
	v_mov_b32_e32 v12, v4
	v_mov_b32_e32 v13, v4
	v_mov_b32_e32 v14, v4
	v_mov_b32_e32 v15, v4
	v_mov_b32_e32 v16, v4
	v_mov_b32_e32 v17, v4
	v_mov_b32_e32 v18, v4
	v_mov_b32_e32 v19, v4
	v_mov_b32_e32 v36, v4
	v_mov_b32_e32 v37, v4
	v_mov_b32_e32 v38, v4
	v_mov_b32_e32 v39, v4
	v_mov_b32_e32 v40, v4
	v_mov_b32_e32 v41, v4
	v_mov_b32_e32 v42, v4
	v_mov_b32_e32 v43, v4
	v_mov_b32_e32 v44, v4
	v_mov_b32_e32 v45, v4
	v_mov_b32_e32 v46, v4
	v_mov_b32_e32 v47, v4
	v_mov_b32_e32 v48, v4
	v_mov_b32_e32 v49, v4
	v_mov_b32_e32 v50, v4
	v_mov_b32_e32 v51, v4
	v_mov_b32_e32 v20, v4
	v_mov_b32_e32 v21, v4
	v_mov_b32_e32 v22, v4
	v_mov_b32_e32 v23, v4
	v_mov_b32_e32 v24, v4
	v_mov_b32_e32 v25, v4
	v_mov_b32_e32 v26, v4
	v_mov_b32_e32 v27, v4
	v_mov_b32_e32 v28, v4
	v_mov_b32_e32 v29, v4
	v_mov_b32_e32 v30, v4
	v_mov_b32_e32 v31, v4
	v_mov_b32_e32 v32, v4
	v_mov_b32_e32 v33, v4
	v_mov_b32_e32 v34, v4
	v_mov_b32_e32 v35, v4
	v_mov_b32_e32 v52, v4
	v_mov_b32_e32 v53, v4
	v_mov_b32_e32 v54, v4
	v_mov_b32_e32 v55, v4
	v_mov_b32_e32 v56, v4
	v_mov_b32_e32 v57, v4
	v_mov_b32_e32 v58, v4
	v_mov_b32_e32 v59, v4
	v_mov_b32_e32 v60, v4
	v_mov_b32_e32 v61, v4
	v_mov_b32_e32 v62, v4
	v_mov_b32_e32 v63, v4
	v_mov_b32_e32 v64, v4
	v_mov_b32_e32 v65, v4
	v_mov_b32_e32 v66, v4
	v_mov_b32_e32 v67, v4
	s_waitcnt lgkmcnt(0)
	s_barrier
	v_mov_b32_e32 v178, v102
	v_mov_b32_e32 v179, v103
	v_add_co_u32_e32 v180, vcc, s38, v102
	s_nop 1
	v_addc_co_u32_e32 v181, vcc, 0, v103, vcc
	v_add_co_u32_e32 v182, vcc, s39, v102
	s_nop 1
	v_addc_co_u32_e32 v183, vcc, 0, v103, vcc
	v_add_co_u32_e32 v184, vcc, s42, v102
	s_nop 1
	v_addc_co_u32_e32 v185, vcc, 0, v103, vcc
	v_add_co_u32_e32 v186, vcc, s43, v104
	s_mov_b32 s12, 0x2ba9000
	s_nop 0
	v_addc_co_u32_e32 v187, vcc, 0, v105, vcc
	v_add_co_u32_e32 v188, vcc, s12, v104
	s_mov_b32 s12, 0x2bba000
	s_nop 0
	v_addc_co_u32_e32 v189, vcc, 0, v105, vcc
	v_add_co_u32_e32 v190, vcc, s12, v104
	s_mov_b32 s12, 0x2bcb000
	s_nop 0
	v_addc_co_u32_e32 v191, vcc, 0, v105, vcc
	v_add_co_u32_e32 v192, vcc, s12, v104
	s_nop 1
	v_addc_co_u32_e32 v193, vcc, 0, v105, vcc
	s_movk_i32 s6, 0x80
	s_mov_b32 s7, 0
	global_load_dwordx4 v[174:177], v[178:179], off offset:256
	global_load_dwordx4 v[194:197], v[180:181], off offset:256
	global_load_dwordx4 v[198:201], v[182:183], off offset:256
	global_load_dwordx4 v[230:233], v[184:185], off offset:256
	global_load_dwordx4 v[240:243], v[186:187], off offset:256
	global_load_dwordx4 v[244:247], v[188:189], off offset:256
	global_load_dwordx4 v[248:251], v[190:191], off offset:256
	global_load_dwordx4 v[102:105], v[192:193], off offset:256
	ds_read_b128 v[154:157], v101
	ds_read_b128 v[162:165], v120 offset:36864
	ds_read_b128 v[150:153], v120 offset:41472
	ds_read_b128 v[122:125], v101 offset:4608

; DI void phase_proj(const Params& p, int layer, char* smem, int xcd, int loc, int nloc) {
;     ...
;   for (int i = loc;; i += nloc) {
;     int mt, nt;
;     if (!tile_order<59>(i, xcd, mt, nt)) break;
.LBB0_1464:
	s_setprio 0
	s_mov_b64 s[0:1], 0
	s_mov_b64 s[48:49], 0x100
